# P1 K-loop: 12 of 16 LDS-DMA loads per iteration use SGPR base + 32-bit VGPR offset instead of a 64-bit VALU address add (fewer VALU per MFMA); rest as v166
# baseline (speedup 1.0000x reference)
; #define PG8_STAGE(bufoff, gbase, voff) do { _Pragma("unroll") for (int _i = 0; _i < 2; ++_i) \
;         __builtin_amdgcn_global_load_lds((const unsigned*)((const char*)(gbase) + (voff)[_i]), (PG8_LAS unsigned*)(lds + (bufoff) + ldsw + _i * 8192), 16, 0, 0); } while (0)
; #define PG8_LDA(dst, b, h) do { _Pragma("unroll") for (int m = 0; m < 4; ++m) _Pragma("unroll") for (int k = 0; k < 2; ++k) dst[m][k] = *(const PG8_LAS bf16x8*)(lds + PG8_SA(b, h) + aoff + m * 2048 + k * 1024); } while (0)
; #define PG8_LDB(dst, b, h) do { _Pragma("unroll") for (int n = 0; n < 2; ++n) _Pragma("unroll") for (int k = 0; k < 2; ++k) dst[n][k] = *(const PG8_LAS bf16x8*)(lds + PG8_SB(b, h) + boff + n * 2048 + k * 1024); } while (0)
; #define PG8_MMA(ai, bj, At, Bt) do { __builtin_amdgcn_s_setprio(1); _Pragma("unroll") for (int m = 0; m < 4; ++m) _Pragma("unroll") for (int n = 0; n < 2; ++n) _Pragma("unroll") for (int k = 0; k < 2; ++k) \
;         acc[ai][bj][m][n] = __builtin_amdgcn_mfma_f32_16x16x32_bf16(Bt[n][k], At[m][k], acc[ai][bj][m][n], 0, 0, 0); __builtin_amdgcn_s_setprio(0); } while (0)
; #define PG8_WAIT_V(n) asm volatile("s_waitcnt vmcnt(" #n ")" ::: "memory")
; #define PG8_WAIT_L(n) asm volatile("s_waitcnt lgkmcnt(" #n ")" ::: "memory")
; #define PG8_BAR __builtin_amdgcn_s_barrier()
; #define PG8_SCHED __builtin_amdgcn_sched_barrier(0)
; template <class Epi, class Sched, bool ALIGN_EPI = false, bool SP2 = false>
; __device__ __forceinline__ void gemm_phase(PG8_LAS unsigned char* lds, const Gemm g, const Sched& S, const Epi& E, const int wave_id) {
;     ...
;             PG8_LDB(B0, 0, 0); PG8_LDB(B1, 0, 1); PG8_SCHED; PG8_LDA(At, 0, 0); PG8_STAGE(PG8_SA(1, 1), a1 + hstep, voffA);
;             PG8_WAIT_V(8); PG8_WAIT_L(0); PG8_BAR; PG8_MMA(0, 0, At, B0); PG8_MMA(0, 1, At, B1); PG8_BAR; PG8_SCHED;
;             PG8_LDA(At, 0, 1); PG8_STAGE(PG8_SB(0, 0), b2, voffB); PG8_STAGE(PG8_SB(0, 1), b2 + hstep, voffB); PG8_STAGE(PG8_SA(0, 0), a2, voffA);
;             PG8_WAIT_V(8); PG8_WAIT_L(0); PG8_BAR; PG8_MMA(1, 0, At, B0); PG8_MMA(1, 1, At, B1); PG8_BAR; PG8_SCHED;
.LBB0_172:
	ds_read_b128 v[148:151], v159
	ds_read_b128 v[152:155], v159 offset:1024
	ds_read_b128 v[162:165], v159 offset:2048
	ds_read_b128 v[166:169], v159 offset:3072
	ds_read_b128 v[170:173], v160
	ds_read_b128 v[174:177], v160 offset:1024
	ds_read_b128 v[178:181], v160 offset:2048
	ds_read_b128 v[182:185], v160 offset:3072
	s_add_u32 s48, s46, 0xfff80080
	s_addc_u32 s49, s47, -1
	s_cmp_eq_u32 s79, 28
	s_cselect_b32 s51, s5, s49
	s_cselect_b32 s50, s7, s48
	s_cselect_b32 s49, s37, s78
	s_cselect_b32 s48, s41, s67
	s_add_i32 m0, s68, 0xc000
	ds_read_b128 v[186:189], v161
	ds_read_b128 v[190:193], v161 offset:1024
	ds_read_b128 v[194:197], v161 offset:2048
	ds_read_b128 v[198:201], v161 offset:3072
	ds_read_b128 v[202:205], v161 offset:4096
	ds_read_b128 v[206:209], v161 offset:5120
	ds_read_b128 v[210:213], v161 offset:6144
	ds_read_b128 v[214:217], v161 offset:7168
	global_load_lds_dwordx4 v138, s[46:47]
	s_add_i32 m0, s68, 0xe000
	s_nop 0
	global_load_lds_dwordx4 v140, s[46:47]
	s_waitcnt vmcnt(8)
	s_waitcnt lgkmcnt(0)
	s_barrier
	s_waitcnt lgkmcnt(0)
	v_mfma_f32_16x16x32_bf16 v[124:127], v[148:151], v[186:189], v[124:127]
	v_mfma_f32_16x16x32_bf16 v[120:123], v[162:165], v[186:189], v[120:123]
	v_mfma_f32_16x16x32_bf16 v[108:111], v[148:151], v[194:197], v[108:111]
	v_mfma_f32_16x16x32_bf16 v[104:107], v[162:165], v[194:197], v[104:107]
	v_mfma_f32_16x16x32_bf16 v[92:95], v[148:151], v[202:205], v[92:95]
	v_mfma_f32_16x16x32_bf16 v[88:91], v[162:165], v[202:205], v[88:91]
	v_mfma_f32_16x16x32_bf16 v[76:79], v[148:151], v[210:213], v[76:79]
	v_mfma_f32_16x16x32_bf16 v[72:75], v[162:165], v[210:213], v[72:75]
	v_mfma_f32_16x16x32_bf16 v[124:127], v[152:155], v[190:193], v[124:127]
	v_mfma_f32_16x16x32_bf16 v[120:123], v[166:169], v[190:193], v[120:123]
	v_mfma_f32_16x16x32_bf16 v[108:111], v[152:155], v[198:201], v[108:111]
	v_mfma_f32_16x16x32_bf16 v[104:107], v[166:169], v[198:201], v[104:107]
	v_mfma_f32_16x16x32_bf16 v[92:95], v[152:155], v[206:209], v[92:95]
	v_mfma_f32_16x16x32_bf16 v[88:91], v[166:169], v[206:209], v[88:91]
	v_mfma_f32_16x16x32_bf16 v[76:79], v[152:155], v[214:217], v[76:79]
	v_mfma_f32_16x16x32_bf16 v[72:75], v[166:169], v[214:217], v[72:75]
	v_mfma_f32_16x16x32_bf16 v[116:119], v[170:173], v[186:189], v[116:119]
	v_mfma_f32_16x16x32_bf16 v[112:115], v[178:181], v[186:189], v[112:115]
	v_mfma_f32_16x16x32_bf16 v[100:103], v[170:173], v[194:197], v[100:103]
	v_mfma_f32_16x16x32_bf16 v[96:99], v[178:181], v[194:197], v[96:99]
	v_mfma_f32_16x16x32_bf16 v[84:87], v[170:173], v[202:205], v[84:87]
	v_mfma_f32_16x16x32_bf16 v[80:83], v[178:181], v[202:205], v[80:83]
	v_mfma_f32_16x16x32_bf16 v[68:71], v[170:173], v[210:213], v[68:71]
	v_mfma_f32_16x16x32_bf16 v[64:67], v[178:181], v[210:213], v[64:67]
	v_mfma_f32_16x16x32_bf16 v[116:119], v[174:177], v[190:193], v[116:119]
	v_mfma_f32_16x16x32_bf16 v[112:115], v[182:185], v[190:193], v[112:115]
	v_mfma_f32_16x16x32_bf16 v[100:103], v[174:177], v[198:201], v[100:103]
	v_mfma_f32_16x16x32_bf16 v[96:99], v[182:185], v[198:201], v[96:99]
	v_mfma_f32_16x16x32_bf16 v[84:87], v[174:177], v[206:209], v[84:87]
	v_mfma_f32_16x16x32_bf16 v[80:83], v[182:185], v[206:209], v[80:83]
	v_mfma_f32_16x16x32_bf16 v[68:71], v[174:177], v[214:217], v[68:71]
	v_mfma_f32_16x16x32_bf16 v[64:67], v[182:185], v[214:217], v[64:67]
	s_barrier
	s_add_i32 s80, s76, s56
	v_lshl_add_u64 v[218:219], s[48:49], 0, v[130:131]
	s_mov_b32 m0, s80
	ds_read_b128 v[186:189], v161 offset:16384
	ds_read_b128 v[190:193], v161 offset:17408
	ds_read_b128 v[194:197], v161 offset:18432
	ds_read_b128 v[198:201], v161 offset:19456
	ds_read_b128 v[202:205], v161 offset:20480
	ds_read_b128 v[206:209], v161 offset:21504
	ds_read_b128 v[210:213], v161 offset:22528
	ds_read_b128 v[214:217], v161 offset:23552
	global_load_lds_dwordx4 v[218:219], off
	s_add_i32 m0, s80, 0x2000
	s_add_u32 s80, s48, 0x80000
	v_lshl_add_u64 v[220:221], s[48:49], 0, v[134:135]
	s_addc_u32 s81, s49, 0
	s_add_i32 s82, s77, s56
	global_load_lds_dwordx4 v[220:221], off
	s_mov_b32 m0, s82
	s_add_u32 s100, s50, s16
	s_addc_u32 s101, s51, s17
	global_load_lds_dwordx4 v130, s[80:81]
	s_add_i32 m0, s82, 0x2000
	s_nop 0
	global_load_lds_dwordx4 v134, s[80:81]
	s_mov_b32 m0, s68
	s_nop 0
	global_load_lds_dwordx4 v128, s[50:51]
	s_mov_b32 m0, s70
	s_nop 0
	global_load_lds_dwordx4 v132, s[50:51]
	s_waitcnt vmcnt(8)
	s_waitcnt lgkmcnt(0)
	s_barrier
	s_waitcnt lgkmcnt(0)
	v_mfma_f32_16x16x32_bf16 v[60:63], v[148:151], v[186:189], v[60:63]
	v_mfma_f32_16x16x32_bf16 v[56:59], v[162:165], v[186:189], v[56:59]
	v_mfma_f32_16x16x32_bf16 v[44:47], v[148:151], v[194:197], v[44:47]
	v_mfma_f32_16x16x32_bf16 v[40:43], v[162:165], v[194:197], v[40:43]
	v_mfma_f32_16x16x32_bf16 v[28:31], v[148:151], v[202:205], v[28:31]
	v_mfma_f32_16x16x32_bf16 v[24:27], v[162:165], v[202:205], v[24:27]
	v_mfma_f32_16x16x32_bf16 v[12:15], v[148:151], v[210:213], v[12:15]
	v_mfma_f32_16x16x32_bf16 v[8:11], v[162:165], v[210:213], v[8:11]
	v_mfma_f32_16x16x32_bf16 v[60:63], v[152:155], v[190:193], v[60:63]
	v_mfma_f32_16x16x32_bf16 v[56:59], v[166:169], v[190:193], v[56:59]
	v_mfma_f32_16x16x32_bf16 v[44:47], v[152:155], v[198:201], v[44:47]
	v_mfma_f32_16x16x32_bf16 v[40:43], v[166:169], v[198:201], v[40:43]
	v_mfma_f32_16x16x32_bf16 v[28:31], v[152:155], v[206:209], v[28:31]
	v_mfma_f32_16x16x32_bf16 v[24:27], v[166:169], v[206:209], v[24:27]
	v_mfma_f32_16x16x32_bf16 v[12:15], v[152:155], v[214:217], v[12:15]
	v_mfma_f32_16x16x32_bf16 v[8:11], v[166:169], v[214:217], v[8:11]
	v_mfma_f32_16x16x32_bf16 v[52:55], v[170:173], v[186:189], v[52:55]
	v_mfma_f32_16x16x32_bf16 v[48:51], v[178:181], v[186:189], v[48:51]
	v_mfma_f32_16x16x32_bf16 v[36:39], v[170:173], v[194:197], v[36:39]
	v_mfma_f32_16x16x32_bf16 v[32:35], v[178:181], v[194:197], v[32:35]
	v_mfma_f32_16x16x32_bf16 v[20:23], v[170:173], v[202:205], v[20:23]
	v_mfma_f32_16x16x32_bf16 v[16:19], v[178:181], v[202:205], v[16:19]
	v_mfma_f32_16x16x32_bf16 v[4:7], v[170:173], v[210:213], v[4:7]
	v_mfma_f32_16x16x32_bf16 v[0:3], v[178:181], v[210:213], v[0:3]
	v_mfma_f32_16x16x32_bf16 v[52:55], v[174:177], v[190:193], v[52:55]
	v_mfma_f32_16x16x32_bf16 v[48:51], v[182:185], v[190:193], v[48:51]
	v_mfma_f32_16x16x32_bf16 v[36:39], v[174:177], v[198:201], v[36:39]
	v_mfma_f32_16x16x32_bf16 v[32:35], v[182:185], v[198:201], v[32:35]
	v_mfma_f32_16x16x32_bf16 v[20:23], v[174:177], v[206:209], v[20:23]
	v_mfma_f32_16x16x32_bf16 v[16:19], v[182:185], v[206:209], v[16:19]
	v_mfma_f32_16x16x32_bf16 v[4:7], v[174:177], v[214:217], v[4:7]
	v_mfma_f32_16x16x32_bf16 v[0:3], v[182:185], v[214:217], v[0:3]
	s_barrier
; #define PG8_STAGE(bufoff, gbase, voff) do { _Pragma("unroll") for (int _i = 0; _i < 2; ++_i) \
;         __builtin_amdgcn_global_load_lds((const unsigned*)((const char*)(gbase) + (voff)[_i]), (PG8_LAS unsigned*)(lds + (bufoff) + ldsw + _i * 8192), 16, 0, 0); } while (0)
; #define PG8_LDA(dst, b, h) do { _Pragma("unroll") for (int m = 0; m < 4; ++m) _Pragma("unroll") for (int k = 0; k < 2; ++k) dst[m][k] = *(const PG8_LAS bf16x8*)(lds + PG8_SA(b, h) + aoff + m * 2048 + k * 1024); } while (0)
; #define PG8_LDB(dst, b, h) do { _Pragma("unroll") for (int n = 0; n < 2; ++n) _Pragma("unroll") for (int k = 0; k < 2; ++k) dst[n][k] = *(const PG8_LAS bf16x8*)(lds + PG8_SB(b, h) + boff + n * 2048 + k * 1024); } while (0)
; #define PG8_MMA(ai, bj, At, Bt) do { __builtin_amdgcn_s_setprio(1); _Pragma("unroll") for (int m = 0; m < 4; ++m) _Pragma("unroll") for (int n = 0; n < 2; ++n) _Pragma("unroll") for (int k = 0; k < 2; ++k) \
;         acc[ai][bj][m][n] = __builtin_amdgcn_mfma_f32_16x16x32_bf16(Bt[n][k], At[m][k], acc[ai][bj][m][n], 0, 0, 0); __builtin_amdgcn_s_setprio(0); } while (0)
; #define PG8_WAIT_V(n) asm volatile("s_waitcnt vmcnt(" #n ")" ::: "memory")
; #define PG8_WAIT_L(n) asm volatile("s_waitcnt lgkmcnt(" #n ")" ::: "memory")
; #define PG8_BAR __builtin_amdgcn_s_barrier()
; #define PG8_SCHED __builtin_amdgcn_sched_barrier(0)
; template <class Epi, class Sched, bool ALIGN_EPI = false, bool SP2 = false>
; __device__ __forceinline__ void gemm_phase(PG8_LAS unsigned char* lds, const Gemm g, const Sched& S, const Epi& E, const int wave_id) {
;     ...
;             PG8_LDB(B0, 1, 0); PG8_LDB(B1, 1, 1); PG8_SCHED; PG8_LDA(At, 1, 0); PG8_STAGE(PG8_SA(0, 1), a2 + hstep, voffA);
;             PG8_WAIT_V(8); PG8_WAIT_L(0); PG8_BAR; PG8_MMA(0, 0, At, B0); PG8_MMA(0, 1, At, B1); PG8_BAR; PG8_SCHED;
;             PG8_LDA(At, 1, 1); PG8_STAGE(PG8_SB(1, 0), b3, voffB); PG8_STAGE(PG8_SB(1, 1), b3 + hstep, voffB); PG8_STAGE(PG8_SA(1, 0), a3, voffA);
;             PG8_WAIT_V(8); PG8_WAIT_L(0); PG8_BAR; PG8_MMA(1, 0, At, B0); PG8_MMA(1, 1, At, B1); PG8_BAR; PG8_SCHED;
	s_add_i32 s80, 0, 0x18000
	v_add_u32_e32 v136, s80, v157
	s_add_i32 s81, 0, 0x1c000
	ds_read_b128 v[148:151], v136
	ds_read_b128 v[152:155], v136 offset:1024
	ds_read_b128 v[162:165], v136 offset:2048
	ds_read_b128 v[166:169], v136 offset:3072
	v_add_u32_e32 v136, s81, v157
	ds_read_b128 v[170:173], v136
	ds_read_b128 v[174:177], v136 offset:1024
	ds_read_b128 v[178:181], v136 offset:2048
	ds_read_b128 v[182:185], v136 offset:3072
	s_add_u32 s50, s50, 0x80000
	s_addc_u32 s51, s51, 0
	s_mov_b32 m0, s71
	ds_read_b128 v[186:189], v161 offset:32768
	ds_read_b128 v[190:193], v161 offset:33792
	ds_read_b128 v[194:197], v161 offset:34816
	ds_read_b128 v[198:201], v161 offset:35840
	ds_read_b128 v[202:205], v161 offset:36864
	ds_read_b128 v[206:209], v161 offset:37888
	ds_read_b128 v[210:213], v161 offset:38912
	ds_read_b128 v[214:217], v161 offset:39936
	global_load_lds_dwordx4 v128, s[50:51]
	s_mov_b32 m0, s72
	s_nop 0
	global_load_lds_dwordx4 v132, s[50:51]
	s_waitcnt vmcnt(8)
	s_waitcnt lgkmcnt(0)
	s_barrier
	s_waitcnt lgkmcnt(0)
	v_mfma_f32_16x16x32_bf16 v[124:127], v[148:151], v[186:189], v[124:127]
	v_mfma_f32_16x16x32_bf16 v[120:123], v[162:165], v[186:189], v[120:123]
	v_mfma_f32_16x16x32_bf16 v[108:111], v[148:151], v[194:197], v[108:111]
	v_mfma_f32_16x16x32_bf16 v[104:107], v[162:165], v[194:197], v[104:107]
	v_mfma_f32_16x16x32_bf16 v[92:95], v[148:151], v[202:205], v[92:95]
	v_mfma_f32_16x16x32_bf16 v[88:91], v[162:165], v[202:205], v[88:91]
	v_mfma_f32_16x16x32_bf16 v[76:79], v[148:151], v[210:213], v[76:79]
	v_mfma_f32_16x16x32_bf16 v[72:75], v[162:165], v[210:213], v[72:75]
	v_mfma_f32_16x16x32_bf16 v[124:127], v[152:155], v[190:193], v[124:127]
	v_mfma_f32_16x16x32_bf16 v[120:123], v[166:169], v[190:193], v[120:123]
	v_mfma_f32_16x16x32_bf16 v[108:111], v[152:155], v[198:201], v[108:111]
	v_mfma_f32_16x16x32_bf16 v[104:107], v[166:169], v[198:201], v[104:107]
	v_mfma_f32_16x16x32_bf16 v[92:95], v[152:155], v[206:209], v[92:95]
	v_mfma_f32_16x16x32_bf16 v[88:91], v[166:169], v[206:209], v[88:91]
	v_mfma_f32_16x16x32_bf16 v[76:79], v[152:155], v[214:217], v[76:79]
	v_mfma_f32_16x16x32_bf16 v[72:75], v[166:169], v[214:217], v[72:75]
	v_mfma_f32_16x16x32_bf16 v[116:119], v[170:173], v[186:189], v[116:119]
	v_mfma_f32_16x16x32_bf16 v[112:115], v[178:181], v[186:189], v[112:115]
	v_mfma_f32_16x16x32_bf16 v[100:103], v[170:173], v[194:197], v[100:103]
	v_mfma_f32_16x16x32_bf16 v[96:99], v[178:181], v[194:197], v[96:99]
	v_mfma_f32_16x16x32_bf16 v[84:87], v[170:173], v[202:205], v[84:87]
	v_mfma_f32_16x16x32_bf16 v[80:83], v[178:181], v[202:205], v[80:83]
	v_mfma_f32_16x16x32_bf16 v[68:71], v[170:173], v[210:213], v[68:71]
	v_mfma_f32_16x16x32_bf16 v[64:67], v[178:181], v[210:213], v[64:67]
	v_mfma_f32_16x16x32_bf16 v[116:119], v[174:177], v[190:193], v[116:119]
	v_mfma_f32_16x16x32_bf16 v[112:115], v[182:185], v[190:193], v[112:115]
	v_mfma_f32_16x16x32_bf16 v[100:103], v[174:177], v[198:201], v[100:103]
	v_mfma_f32_16x16x32_bf16 v[96:99], v[182:185], v[198:201], v[96:99]
	v_mfma_f32_16x16x32_bf16 v[84:87], v[174:177], v[206:209], v[84:87]
	v_mfma_f32_16x16x32_bf16 v[80:83], v[182:185], v[206:209], v[80:83]
	v_mfma_f32_16x16x32_bf16 v[68:71], v[174:177], v[214:217], v[68:71]
	v_mfma_f32_16x16x32_bf16 v[64:67], v[182:185], v[214:217], v[64:67]
	s_barrier
	s_add_i32 s50, s80, s56
	v_lshl_add_u64 v[218:219], v[218:219], 0, s[16:17]
	s_mov_b32 m0, s50
	ds_read_b128 v[186:189], v161 offset:49152
	ds_read_b128 v[190:193], v161 offset:50176
	ds_read_b128 v[194:197], v161 offset:51200
	ds_read_b128 v[198:201], v161 offset:52224
	ds_read_b128 v[202:205], v161 offset:53248
	ds_read_b128 v[206:209], v161 offset:54272
	ds_read_b128 v[210:213], v161 offset:55296
	ds_read_b128 v[214:217], v161 offset:56320
	global_load_lds_dwordx4 v[218:219], off
	s_add_i32 m0, s50, 0x2000
	s_add_u32 s48, s48, 0x80080
	v_lshl_add_u64 v[218:219], v[220:221], 0, s[16:17]
	s_addc_u32 s49, s49, 0
	s_add_i32 s50, s81, s56
	global_load_lds_dwordx4 v[218:219], off
	s_mov_b32 m0, s50
	s_nop 0
	global_load_lds_dwordx4 v130, s[48:49]
	s_add_i32 m0, s50, 0x2000
	s_nop 0
	global_load_lds_dwordx4 v134, s[48:49]
	s_mov_b32 m0, s73
	s_nop 0
	global_load_lds_dwordx4 v128, s[100:101]
	s_mov_b32 m0, s74
	s_nop 0
	global_load_lds_dwordx4 v132, s[100:101]
	s_waitcnt vmcnt(8)
	s_waitcnt lgkmcnt(0)
	s_barrier
	s_waitcnt lgkmcnt(0)
	v_mfma_f32_16x16x32_bf16 v[60:63], v[148:151], v[186:189], v[60:63]
	v_mfma_f32_16x16x32_bf16 v[56:59], v[162:165], v[186:189], v[56:59]
	v_mfma_f32_16x16x32_bf16 v[44:47], v[148:151], v[194:197], v[44:47]
	v_mfma_f32_16x16x32_bf16 v[40:43], v[162:165], v[194:197], v[40:43]
	v_mfma_f32_16x16x32_bf16 v[28:31], v[148:151], v[202:205], v[28:31]
	v_mfma_f32_16x16x32_bf16 v[24:27], v[162:165], v[202:205], v[24:27]
	v_mfma_f32_16x16x32_bf16 v[12:15], v[148:151], v[210:213], v[12:15]
	v_mfma_f32_16x16x32_bf16 v[8:11], v[162:165], v[210:213], v[8:11]
	v_mfma_f32_16x16x32_bf16 v[60:63], v[152:155], v[190:193], v[60:63]
	v_mfma_f32_16x16x32_bf16 v[56:59], v[166:169], v[190:193], v[56:59]
	v_mfma_f32_16x16x32_bf16 v[44:47], v[152:155], v[198:201], v[44:47]
	v_mfma_f32_16x16x32_bf16 v[40:43], v[166:169], v[198:201], v[40:43]
	v_mfma_f32_16x16x32_bf16 v[28:31], v[152:155], v[206:209], v[28:31]
	v_mfma_f32_16x16x32_bf16 v[24:27], v[166:169], v[206:209], v[24:27]
	v_mfma_f32_16x16x32_bf16 v[12:15], v[152:155], v[214:217], v[12:15]
	v_mfma_f32_16x16x32_bf16 v[8:11], v[166:169], v[214:217], v[8:11]
	v_mfma_f32_16x16x32_bf16 v[52:55], v[170:173], v[186:189], v[52:55]
	v_mfma_f32_16x16x32_bf16 v[48:51], v[178:181], v[186:189], v[48:51]
	v_mfma_f32_16x16x32_bf16 v[36:39], v[170:173], v[194:197], v[36:39]
	v_mfma_f32_16x16x32_bf16 v[32:35], v[178:181], v[194:197], v[32:35]
	v_mfma_f32_16x16x32_bf16 v[20:23], v[170:173], v[202:205], v[20:23]
	v_mfma_f32_16x16x32_bf16 v[16:19], v[178:181], v[202:205], v[16:19]
	v_mfma_f32_16x16x32_bf16 v[4:7], v[170:173], v[210:213], v[4:7]
	v_mfma_f32_16x16x32_bf16 v[0:3], v[178:181], v[210:213], v[0:3]
	v_mfma_f32_16x16x32_bf16 v[52:55], v[174:177], v[190:193], v[52:55]
	v_mfma_f32_16x16x32_bf16 v[48:51], v[182:185], v[190:193], v[48:51]
	v_mfma_f32_16x16x32_bf16 v[36:39], v[174:177], v[198:201], v[36:39]
	v_mfma_f32_16x16x32_bf16 v[32:35], v[182:185], v[198:201], v[32:35]
	v_mfma_f32_16x16x32_bf16 v[20:23], v[174:177], v[206:209], v[20:23]
	v_mfma_f32_16x16x32_bf16 v[16:19], v[182:185], v[206:209], v[16:19]
	v_mfma_f32_16x16x32_bf16 v[4:7], v[174:177], v[214:217], v[4:7]
	v_mfma_f32_16x16x32_bf16 v[0:3], v[182:185], v[214:217], v[0:3]
	s_barrier
	s_add_i32 s79, s79, 2
	s_add_u32 s46, s46, 0x100
	s_addc_u32 s47, s47, 0
	s_add_u32 s67, s67, 0x100
	s_addc_u32 s78, s78, 0
	s_cmp_gt_u32 s79, 29
	s_cbranch_scc0 .LBB0_172
	s_and_b64 vcc, exec, s[24:25]
	s_cbranch_vccz .LBB0_175
	s_barrier
